# grid barrier: leader publishes XGEN before its own L1 invalidate; first-barrier counter loads issued together
# speedup vs baseline: 1.0054x; 1.0054x over previous
; __device__ __forceinline__ unsigned xb_ld(unsigned* p)              { return __hip_atomic_load(p, __ATOMIC_RELAXED, __HIP_MEMORY_SCOPE_AGENT); }
; __device__ __forceinline__ void xcd_barrier_complete(unsigned* bar, unsigned x, unsigned& nloc, unsigned& nx) {
;     const unsigned G = gridDim.x * gridDim.y * gridDim.z;
;     unsigned sum, cnt, mine, sp = 0u;
;     for (;;) {
;         sum = 0u; cnt = 0u; mine = 0u;
; #pragma unroll
;         for (unsigned j = 0; j < 16; ++j) { const unsigned c = xb_ld(&bar[XB_XCNT(j)]); sum += c; cnt += (c > 0u) ? 1u : 0u; mine = (j == x) ? c : mine; }
;         if (sum == G) break;
;         __builtin_amdgcn_s_sleep(1);
;         if ((++sp & 255u) == 0u) { if (xb_ld(&bar[XB_TMO])) break; if (sp > XB_SPIN_CAP) { atomicAdd(&bar[XB_TMO], 1u); break; } }
;     }
;     nloc = mine > 0u ? mine : 1u; nx = cnt > 0u ? cnt : 1u;
; }
.LBB0_618:
	v_readlane_b32 s6, v252, 38
	v_readlane_b32 s7, v252, 39
	s_mov_b64 s[8:9], -1
	s_nop 3
	global_load_dword v0, v183, s[6:7] sc1
	v_readlane_b32 s6, v252, 40
	v_readlane_b32 s7, v252, 41
	s_nop 4
	global_load_dword v1, v183, s[6:7] sc1
	v_readlane_b32 s6, v252, 42
	v_readlane_b32 s7, v252, 43
	s_nop 4
	global_load_dword v2, v183, s[6:7] sc1
	v_readlane_b32 s6, v252, 44
	v_readlane_b32 s7, v252, 45
	s_nop 4
	global_load_dword v3, v183, s[6:7] sc1
	v_readlane_b32 s6, v252, 46
	v_readlane_b32 s7, v252, 47
	s_nop 4
	global_load_dword v4, v183, s[6:7] sc1
	v_readlane_b32 s6, v252, 48
	v_readlane_b32 s7, v252, 49
	s_nop 4
	global_load_dword v5, v183, s[6:7] sc1
	v_readlane_b32 s6, v252, 50
	v_readlane_b32 s7, v252, 51
	s_nop 4
	global_load_dword v6, v183, s[6:7] sc1
	v_readlane_b32 s6, v252, 52
	v_readlane_b32 s7, v252, 53
	s_nop 4
	global_load_dword v7, v183, s[6:7] sc1
	v_readlane_b32 s6, v252, 54
	v_readlane_b32 s7, v252, 55
	s_nop 4
	global_load_dword v8, v183, s[6:7] sc1
	v_readlane_b32 s6, v252, 56
	v_readlane_b32 s7, v252, 57
	s_nop 4
	global_load_dword v9, v183, s[6:7] sc1
	v_readlane_b32 s6, v252, 58
	v_readlane_b32 s7, v252, 59
	s_nop 4
	global_load_dword v10, v183, s[6:7] sc1
	v_readlane_b32 s6, v252, 60
	v_readlane_b32 s7, v252, 61
	s_nop 4
	global_load_dword v11, v183, s[6:7] sc1
	v_readlane_b32 s6, v252, 62
	v_readlane_b32 s7, v252, 63
	s_nop 4
	global_load_dword v12, v183, s[6:7] sc1
	v_readlane_b32 s6, v253, 0
	v_readlane_b32 s7, v253, 1
	s_nop 4
	global_load_dword v13, v183, s[6:7] sc1
	v_readlane_b32 s6, v253, 2
	v_readlane_b32 s7, v253, 3
	s_nop 4
	global_load_dword v14, v183, s[6:7] sc1
	v_readlane_b32 s6, v253, 4
	v_readlane_b32 s7, v253, 5
	s_nop 4
	global_load_dword v15, v183, s[6:7] sc1
	s_mov_b64 s[6:7], -1
	s_waitcnt vmcnt(0)
	v_add_u32_e32 v16, v1, v0
	v_add_u32_e32 v16, v16, v2
	v_add_u32_e32 v16, v16, v3
	v_add_u32_e32 v16, v16, v4
	v_add_u32_e32 v16, v16, v5
	v_add_u32_e32 v16, v16, v6
	v_add_u32_e32 v16, v16, v7
	v_add_u32_e32 v16, v16, v8
	v_add_u32_e32 v16, v16, v9
	v_add_u32_e32 v16, v16, v10
	v_add_u32_e32 v16, v16, v11
	v_add_u32_e32 v16, v16, v12
	v_add_u32_e32 v16, v16, v13
	v_add_u32_e32 v16, v16, v14
	v_add_u32_e32 v16, v16, v15
	v_cmp_eq_u32_e32 vcc, s12, v16
	s_cbranch_vccnz .LBB0_617
	s_and_b32 s6, s13, 0xff
	s_cmp_eq_u32 s6, 0
	s_mov_b64 s[6:7], -1
	s_mov_b64 s[10:11], -1
	s_sleep 1
	s_cbranch_scc1 .LBB0_622
	s_and_b64 vcc, exec, s[10:11]
	s_cbranch_vccz .LBB0_617

; __device__ __forceinline__ unsigned xb_add(unsigned* p, unsigned v) { return __hip_atomic_fetch_add(p, v, __ATOMIC_RELAXED, __HIP_MEMORY_SCOPE_AGENT); }
; __device__ __forceinline__ void xcd_barrier(const XcdBarrier& b) {
;     ...
;             __builtin_amdgcn_fence(__ATOMIC_ACQUIRE, "agent");
;             xb_add(&bar[XB_XGEN(b.x)], 1u);
;             asm volatile("s_waitcnt vmcnt(0)" ::: "memory");
.LBB0_664:
	s_or_b64 exec, exec, s[6:7]
	s_mov_b64 s[6:7], exec
	v_mbcnt_lo_u32_b32 v0, s6, 0
	v_mbcnt_hi_u32_b32 v0, s7, v0
	v_cmp_eq_u32_e32 vcc, 0, v0
	s_waitcnt vmcnt(0)
	s_and_saveexec_b64 s[8:9], vcc
	s_cbranch_execz .LBB0_666
	s_bcnt1_i32_b64 s6, s[6:7]
	v_mov_b32_e32 v0, s6
	v_readlane_b32 s6, v253, 40
	v_readlane_b32 s7, v253, 41
	s_nop 4
	global_atomic_add v183, v0, s[6:7]
.LBB0_666:
	s_or_b64 exec, exec, s[8:9]
	buffer_inv sc1
	s_waitcnt vmcnt(0)
